# FFN gate/up: leading half's epilogue-alignment barrier moved to the middle of its epilogue so its first half overlaps the trailing half's last MFMA block
# baseline (speedup 1.0000x reference)
; #define PG8_LAS __attribute__((address_space(3)))
; __host__ __device__ __forceinline__ size_t tiled_off(int row, int col, int K) { return ((size_t)(row >> 7) * (K >> 6) + (col >> 6)) * 8192 + (lds_byte(row & 127, col & 63) >> 1); }
; __device__ __forceinline__ unsigned cvt_pk_bf16(float lo, float hi) { unsigned r; asm volatile("v_cvt_pk_bf16_f32 %0, %1, %2" : "=v"(r) : "v"(lo), "v"(hi)); return r; }
; __device__ __forceinline__ float fast_sigmoid(float x) { return __builtin_amdgcn_rcpf(1.0f + __builtin_amdgcn_exp2f(x * -1.4426950408889634f)); }
;     __device__ __forceinline__ void operator()(const f32x4 (&acc)[2][2][4][2], const Unit& u, int wr, int wc, int fr, int fq, const PG8_LAS float* rtab) const {
;         const int row0 = u.pm * BM + wr * 64 + fr, lcol = u.pn * HALF + wc * 32 + 8 * fq;
;         float rs[2][4]; load_rstd(rtab, wr, fr, rs);
;         f32x4 bv[2], bg[2];
; #pragma unroll
;         for (int n = 0; n < 2; ++n) { bv[n] = (MODE == 0) ? *(const f32x4*)(b0 + lcol + 4 * n) : (f32x4){0.f, 0.f, 0.f, 0.f}; bg[n] = (MODE == 0) ? *(const f32x4*)(b1 + lcol + 4 * n) : (f32x4){0.f, 0.f, 0.f, 0.f}; }
; #pragma unroll
;         for (int ai = 0; ai < 2; ++ai)
; #pragma unroll
;             for (int m = 0; m < 4; ++m) { const float r = rs[ai][m]; float o[8];
; #pragma unroll
;                 for (int n = 0; n < 2; ++n) { const f32x4 a = acc[ai][0][m][n] * r + bv[n], g = acc[ai][1][m][n] * r + bg[n];
; #pragma unroll
;                     for (int e = 0; e < 4; ++e) o[4 * n + e] = (MODE == 0) ? a[e] * fast_sigmoid(g[e]) : a[e] * fast_sigmoid(a[e]) * g[e]; }
;                 u32x4 w; w.x = cvt_pk_bf16(o[0], o[1]); w.y = cvt_pk_bf16(o[2], o[3]); w.z = cvt_pk_bf16(o[4], o[5]); w.w = cvt_pk_bf16(o[6], o[7]);
;                 if (MODE == 1) *(u32x4*)(O + tiled_off(row0 + ai * HALF + m * 16, lcol, ldc)) = w;
;                 else *(u32x4*)(O + (size_t)(row0 + ai * HALF + m * 16) * ldc + lcol) = w; }
; template <class Epi, class Sched, bool ALIGN_EPI = false, bool SP2 = false, bool TA = true>
; __device__ __forceinline__ void gemm_phase(PG8_LAS unsigned char* lds, const Gemm g, const Sched& S, const Epi& E) {
;     ...
;         if constexpr (ALIGN_EPI) { if (wr == 0) PG8_BAR; }
;         if constexpr (!Epi::AFTER_DRAIN) { E(acc, cur, wr, wc, fr, fq, (const PG8_LAS float*)(lds + STAGE_BYTES + 1024 + (ui & 1) * 1024)); S.done(cur); }
.LBB0_793:
	s_lshl_b32 s53, s61, 10
	s_and_b32 s55, s53, 0x400
	v_add_u32_e32 v130, s55, v146
	ds_read2_b32 v[152:153], v130 offset1:16
	ds_read2_b32 v[140:141], v130 offset0:32 offset1:48
	ds_read2_b32 v[138:139], v130 offset0:128 offset1:144
	ds_read2_b32 v[136:137], v130 offset0:160 offset1:176
	s_waitcnt lgkmcnt(0)
	s_lshl_b32 s53, s60, 8
	s_add_i32 s53, s53, s38
	v_or_b32_e32 v151, s53, v142
	v_mul_f32_e32 v224, 0xbfb8aa3b, v152
	v_mul_f32_e32 v225, v152, v152
	v_mul_f32_e32 v234, v124, v224
	v_mul_f32_e32 v235, v125, v224
	v_mul_f32_e32 v236, v126, v224
	v_mul_f32_e32 v237, v127, v224
	v_mul_f32_e32 v238, v116, v224
	v_mul_f32_e32 v239, v117, v224
	v_mul_f32_e32 v240, v118, v224
	v_mul_f32_e32 v241, v119, v224
	v_mul_f32_e32 v226, v124, v120
	v_mul_f32_e32 v227, v125, v121
	v_mul_f32_e32 v228, v126, v122
	v_mul_f32_e32 v229, v127, v123
	v_mul_f32_e32 v230, v116, v112
	v_mul_f32_e32 v231, v117, v113
	v_mul_f32_e32 v232, v118, v114
	v_mul_f32_e32 v233, v119, v115
	v_exp_f32_e32 v234, v234
	v_exp_f32_e32 v235, v235
	v_exp_f32_e32 v236, v236
	v_exp_f32_e32 v237, v237
	v_exp_f32_e32 v238, v238
	v_exp_f32_e32 v239, v239
	v_exp_f32_e32 v240, v240
	v_exp_f32_e32 v241, v241
	v_mul_f32_e32 v226, v226, v225
	v_mul_f32_e32 v227, v227, v225
	v_mul_f32_e32 v228, v228, v225
	v_mul_f32_e32 v229, v229, v225
	v_mul_f32_e32 v230, v230, v225
	v_mul_f32_e32 v231, v231, v225
	v_mul_f32_e32 v232, v232, v225
	v_mul_f32_e32 v233, v233, v225
	v_add_f32_e32 v234, 1.0, v234
	v_add_f32_e32 v235, 1.0, v235
	v_add_f32_e32 v236, 1.0, v236
	v_add_f32_e32 v237, 1.0, v237
	v_add_f32_e32 v238, 1.0, v238
	v_add_f32_e32 v239, 1.0, v239
	v_add_f32_e32 v240, 1.0, v240
	v_add_f32_e32 v241, 1.0, v241
	v_rcp_f32_e32 v234, v234
	v_rcp_f32_e32 v235, v235
	v_rcp_f32_e32 v236, v236
	v_rcp_f32_e32 v237, v237
	v_rcp_f32_e32 v238, v238
	v_rcp_f32_e32 v239, v239
	v_rcp_f32_e32 v240, v240
	v_rcp_f32_e32 v241, v241
	v_mul_f32_e32 v226, v226, v234
	v_mul_f32_e32 v227, v227, v235
	v_mul_f32_e32 v228, v228, v236
	v_mul_f32_e32 v229, v229, v237
	v_mul_f32_e32 v230, v230, v238
	v_mul_f32_e32 v231, v231, v239
	v_mul_f32_e32 v232, v232, v240
	v_mul_f32_e32 v233, v233, v241
	v_cvt_pk_bf16_f32 v242, v226, v227
	v_cvt_pk_bf16_f32 v243, v228, v229
	v_cvt_pk_bf16_f32 v244, v230, v231
	v_cvt_pk_bf16_f32 v245, v232, v233
	v_lshlrev_b32_e32 v116, 6, v151
	v_and_or_b32 v118, v116, s40, v143
	v_lshlrev_b32_e32 v116, 2, v151
	v_and_b32_e32 v119, 32, v116
	s_lshl_b32 s55, s68, 7
	s_or_b32 s55, s55, s39
	s_ashr_i32 s60, s55, 6
	s_ashr_i32 s55, s53, 7
	s_mul_i32 s55, s55, 44
	s_ashr_i32 s61, s60, 31
	s_ashr_i32 s69, s55, 31
	s_add_u32 s68, s55, s60
	s_addc_u32 s69, s69, s61
	s_lshl_b64 s[68:69], s[68:69], 14
	s_add_u32 s68, s14, s68
	v_bitop3_b32 v120, v118, s42, v119 bitop3:0xde
	s_addc_u32 s69, s15, s69
	global_store_dwordx4 v120, v[242:245], s[68:69]
	s_or_b32 s55, s53, 16
	s_lshr_b32 s55, s55, 3
	s_and_b32 s55, s55, 10
	s_or_b32 s55, s55, s41
	s_lshl_b32 s55, s55, 10
	v_mul_f32_e32 v224, 0xbfb8aa3b, v140
	v_mul_f32_e32 v225, v140, v140
	v_mul_f32_e32 v234, v92, v224
	v_mul_f32_e32 v235, v93, v224
	v_mul_f32_e32 v236, v94, v224
	v_mul_f32_e32 v237, v95, v224
	v_mul_f32_e32 v238, v84, v224
	v_mul_f32_e32 v239, v85, v224
	v_mul_f32_e32 v240, v86, v224
	v_mul_f32_e32 v241, v87, v224
	v_mul_f32_e32 v226, v92, v88
	v_mul_f32_e32 v227, v93, v89
	v_mul_f32_e32 v228, v94, v90
	v_mul_f32_e32 v229, v95, v91
	v_mul_f32_e32 v230, v84, v80
	v_mul_f32_e32 v231, v85, v81
	v_mul_f32_e32 v232, v86, v82
	v_mul_f32_e32 v233, v87, v83
	v_exp_f32_e32 v234, v234
	v_exp_f32_e32 v235, v235
	v_exp_f32_e32 v236, v236
	v_exp_f32_e32 v237, v237
	v_exp_f32_e32 v238, v238
	v_exp_f32_e32 v239, v239
	v_exp_f32_e32 v240, v240
	v_exp_f32_e32 v241, v241
	v_mul_f32_e32 v226, v226, v225
	v_mul_f32_e32 v227, v227, v225
	v_mul_f32_e32 v228, v228, v225
	v_mul_f32_e32 v229, v229, v225
	v_mul_f32_e32 v230, v230, v225
	v_mul_f32_e32 v231, v231, v225
	v_mul_f32_e32 v232, v232, v225
	v_mul_f32_e32 v233, v233, v225
	v_add_f32_e32 v234, 1.0, v234
	v_add_f32_e32 v235, 1.0, v235
	v_add_f32_e32 v236, 1.0, v236
	v_add_f32_e32 v237, 1.0, v237
	v_add_f32_e32 v238, 1.0, v238
	v_add_f32_e32 v239, 1.0, v239
	v_add_f32_e32 v240, 1.0, v240
	v_add_f32_e32 v241, 1.0, v241
	v_rcp_f32_e32 v234, v234
	v_rcp_f32_e32 v235, v235
	v_rcp_f32_e32 v236, v236
	v_rcp_f32_e32 v237, v237
	v_rcp_f32_e32 v238, v238
	v_rcp_f32_e32 v239, v239
	v_rcp_f32_e32 v240, v240
	v_rcp_f32_e32 v241, v241
	v_mul_f32_e32 v226, v226, v234
	v_mul_f32_e32 v227, v227, v235
	v_mul_f32_e32 v228, v228, v236
	v_mul_f32_e32 v229, v229, v237
	v_mul_f32_e32 v230, v230, v238
	v_mul_f32_e32 v231, v231, v239
	v_mul_f32_e32 v232, v232, v240
	v_mul_f32_e32 v233, v233, v241
	v_cvt_pk_bf16_f32 v250, v226, v227
	v_cvt_pk_bf16_f32 v251, v228, v229
	v_cvt_pk_bf16_f32 v252, v230, v231
	v_cvt_pk_bf16_f32 v253, v232, v233
	v_bitop3_b32 v93, v118, s55, v119 bitop3:0xde
	v_mul_f32_e32 v224, 0xbfb8aa3b, v153
	v_mul_f32_e32 v225, v153, v153
	v_mul_f32_e32 v234, v108, v224
	v_mul_f32_e32 v235, v109, v224
	v_mul_f32_e32 v236, v110, v224
	v_mul_f32_e32 v237, v111, v224
	v_mul_f32_e32 v238, v100, v224
	v_mul_f32_e32 v239, v101, v224
	v_mul_f32_e32 v240, v102, v224
	v_mul_f32_e32 v241, v103, v224
	v_mul_f32_e32 v226, v108, v104
	v_mul_f32_e32 v227, v109, v105
	v_mul_f32_e32 v228, v110, v106
	v_mul_f32_e32 v229, v111, v107
	v_mul_f32_e32 v230, v100, v96
	v_mul_f32_e32 v231, v101, v97
	v_mul_f32_e32 v232, v102, v98
	v_mul_f32_e32 v233, v103, v99
	v_exp_f32_e32 v234, v234
	v_exp_f32_e32 v235, v235
	v_exp_f32_e32 v236, v236
	v_exp_f32_e32 v237, v237
	v_exp_f32_e32 v238, v238
	v_exp_f32_e32 v239, v239
	v_exp_f32_e32 v240, v240
; __host__ __device__ __forceinline__ size_t tiled_off(int row, int col, int K) { return ((size_t)(row >> 7) * (K >> 6) + (col >> 6)) * 8192 + (lds_byte(row & 127, col & 63) >> 1); }
; __device__ __forceinline__ unsigned cvt_pk_bf16(float lo, float hi) { unsigned r; asm volatile("v_cvt_pk_bf16_f32 %0, %1, %2" : "=v"(r) : "v"(lo), "v"(hi)); return r; }
; __device__ __forceinline__ float fast_sigmoid(float x) { return __builtin_amdgcn_rcpf(1.0f + __builtin_amdgcn_exp2f(x * -1.4426950408889634f)); }
; #define PG8_BAR __builtin_amdgcn_s_barrier()
;     __device__ __forceinline__ void operator()(const f32x4 (&acc)[2][2][4][2], const Unit& u, int wr, int wc, int fr, int fq, const PG8_LAS float* rtab) const {
;     ...
;             for (int m = 0; m < 4; ++m) { const float r = rs[ai][m]; float o[8];
; #pragma unroll
;                 for (int n = 0; n < 2; ++n) { const f32x4 a = acc[ai][0][m][n] * r + bv[n], g = acc[ai][1][m][n] * r + bg[n];
; #pragma unroll
;                     for (int e = 0; e < 4; ++e) o[4 * n + e] = (MODE == 0) ? a[e] * fast_sigmoid(g[e]) : a[e] * fast_sigmoid(a[e]) * g[e]; }
;                 u32x4 w; w.x = cvt_pk_bf16(o[0], o[1]); w.y = cvt_pk_bf16(o[2], o[3]); w.z = cvt_pk_bf16(o[4], o[5]); w.w = cvt_pk_bf16(o[6], o[7]);
;                 if (MODE == 1) *(u32x4*)(O + tiled_off(row0 + ai * HALF + m * 16, lcol, ldc)) = w;
;                 else *(u32x4*)(O + (size_t)(row0 + ai * HALF + m * 16) * ldc + lcol) = w; }
; template <class Epi, class Sched, bool ALIGN_EPI = false, bool SP2 = false, bool TA = true>
; __device__ __forceinline__ void gemm_phase(PG8_LAS unsigned char* lds, const Gemm g, const Sched& S, const Epi& E) {
;     ...
;         if constexpr (ALIGN_EPI) { if (wr == 0) PG8_BAR; }
	v_exp_f32_e32 v241, v241
	v_mul_f32_e32 v226, v226, v225
	v_mul_f32_e32 v227, v227, v225
	v_mul_f32_e32 v228, v228, v225
	v_mul_f32_e32 v229, v229, v225
	v_mul_f32_e32 v230, v230, v225
	v_mul_f32_e32 v231, v231, v225
	v_mul_f32_e32 v232, v232, v225
	v_mul_f32_e32 v233, v233, v225
	v_add_f32_e32 v234, 1.0, v234
	v_add_f32_e32 v235, 1.0, v235
	v_add_f32_e32 v236, 1.0, v236
	v_add_f32_e32 v237, 1.0, v237
	v_add_f32_e32 v238, 1.0, v238
	v_add_f32_e32 v239, 1.0, v239
	v_add_f32_e32 v240, 1.0, v240
	v_add_f32_e32 v241, 1.0, v241
	v_rcp_f32_e32 v234, v234
	v_rcp_f32_e32 v235, v235
	v_rcp_f32_e32 v236, v236
	v_rcp_f32_e32 v237, v237
	v_rcp_f32_e32 v238, v238
	v_rcp_f32_e32 v239, v239
	v_rcp_f32_e32 v240, v240
	v_rcp_f32_e32 v241, v241
	v_mul_f32_e32 v226, v226, v234
	v_mul_f32_e32 v227, v227, v235
	v_mul_f32_e32 v228, v228, v236
	v_mul_f32_e32 v229, v229, v237
	v_mul_f32_e32 v230, v230, v238
	v_mul_f32_e32 v231, v231, v239
	v_mul_f32_e32 v232, v232, v240
	v_mul_f32_e32 v233, v233, v241
	v_cvt_pk_bf16_f32 v246, v226, v227
	v_cvt_pk_bf16_f32 v247, v228, v229
	v_cvt_pk_bf16_f32 v248, v230, v231
	v_cvt_pk_bf16_f32 v249, v232, v233
	global_store_dwordx4 v93, v[246:249], s[68:69]
	s_or_b32 s55, s53, 32
	s_lshr_b32 s55, s55, 3
	s_and_b32 s55, s55, 12
	s_or_b32 s55, s55, s41
	s_lshl_b32 s55, s55, 10
	v_bitop3_b32 v87, v118, s55, v119 bitop3:0xde
	global_store_dwordx4 v87, v[250:253], s[68:69]
	s_or_b32 s53, s53, 48
	s_lshr_b32 s53, s53, 3
	s_and_b32 s53, s53, 14
	s_or_b32 s53, s53, s41
	s_lshl_b32 s53, s53, 10
	v_mul_f32_e32 v224, 0xbfb8aa3b, v141
	v_mul_f32_e32 v225, v141, v141
	v_mul_f32_e32 v234, v76, v224
	v_mul_f32_e32 v235, v77, v224
	v_mul_f32_e32 v236, v78, v224
	v_mul_f32_e32 v237, v79, v224
	v_mul_f32_e32 v238, v68, v224
	v_mul_f32_e32 v239, v69, v224
	v_mul_f32_e32 v240, v70, v224
	v_mul_f32_e32 v241, v71, v224
	v_mul_f32_e32 v226, v76, v72
	v_mul_f32_e32 v227, v77, v73
	v_mul_f32_e32 v228, v78, v74
	v_mul_f32_e32 v229, v79, v75
	v_mul_f32_e32 v230, v68, v64
	v_mul_f32_e32 v231, v69, v65
	v_mul_f32_e32 v232, v70, v66
	v_mul_f32_e32 v233, v71, v67
	v_exp_f32_e32 v234, v234
	v_exp_f32_e32 v235, v235
	v_exp_f32_e32 v236, v236
	v_exp_f32_e32 v237, v237
	v_exp_f32_e32 v238, v238
	v_exp_f32_e32 v239, v239
	v_exp_f32_e32 v240, v240
	v_exp_f32_e32 v241, v241
	v_mul_f32_e32 v226, v226, v225
	v_mul_f32_e32 v227, v227, v225
	v_mul_f32_e32 v228, v228, v225
	v_mul_f32_e32 v229, v229, v225
	v_mul_f32_e32 v230, v230, v225
	v_mul_f32_e32 v231, v231, v225
	v_mul_f32_e32 v232, v232, v225
	v_mul_f32_e32 v233, v233, v225
	v_add_f32_e32 v234, 1.0, v234
	v_add_f32_e32 v235, 1.0, v235
	v_add_f32_e32 v236, 1.0, v236
	v_add_f32_e32 v237, 1.0, v237
	v_add_f32_e32 v238, 1.0, v238
	v_add_f32_e32 v239, 1.0, v239
	v_add_f32_e32 v240, 1.0, v240
	v_add_f32_e32 v241, 1.0, v241
	v_rcp_f32_e32 v234, v234
	v_rcp_f32_e32 v235, v235
	v_rcp_f32_e32 v236, v236
	v_rcp_f32_e32 v237, v237
	v_rcp_f32_e32 v238, v238
	v_rcp_f32_e32 v239, v239
	v_rcp_f32_e32 v240, v240
	v_rcp_f32_e32 v241, v241
	v_mul_f32_e32 v226, v226, v234
	v_mul_f32_e32 v227, v227, v235
	v_mul_f32_e32 v228, v228, v236
	v_mul_f32_e32 v229, v229, v237
	v_mul_f32_e32 v230, v230, v238
	v_mul_f32_e32 v231, v231, v239
	v_mul_f32_e32 v232, v232, v240
	v_mul_f32_e32 v233, v233, v241
	v_cvt_pk_bf16_f32 v242, v226, v227
	v_cvt_pk_bf16_f32 v243, v228, v229
	v_cvt_pk_bf16_f32 v244, v230, v231
	v_cvt_pk_bf16_f32 v245, v232, v233
	v_bitop3_b32 v68, v118, s53, v119 bitop3:0xde
	global_store_dwordx4 v68, v[242:245], s[68:69]
	s_and_b64 vcc, exec, s[50:51]
	s_cbranch_vccz .Lalign_up0
	s_barrier
.Lalign_up0:
	s_andn2_b64 vcc, exec, s[4:5]
	s_mov_b64 s[4:5], -1
	v_add_u32_e32 v67, 0x80, v151
	v_ashrrev_i32_e32 v66, 7, v67
	v_mul_f32_e32 v224, 0xbfb8aa3b, v138
	v_mul_f32_e32 v225, v138, v138
	v_mul_f32_e32 v234, v60, v224
	v_mul_f32_e32 v235, v61, v224
	v_mul_f32_e32 v236, v62, v224
	v_mul_f32_e32 v237, v63, v224
	v_mul_f32_e32 v238, v52, v224
	v_mul_f32_e32 v239, v53, v224
	v_mul_f32_e32 v240, v54, v224
	v_mul_f32_e32 v241, v55, v224
	v_mul_f32_e32 v226, v60, v56
	v_mul_f32_e32 v227, v61, v57
	v_mul_f32_e32 v228, v62, v58
	v_mul_f32_e32 v229, v63, v59
	v_mul_f32_e32 v230, v52, v48
	v_mul_f32_e32 v231, v53, v49
	v_mul_f32_e32 v232, v54, v50
	v_mul_f32_e32 v233, v55, v51
	v_exp_f32_e32 v234, v234
	v_exp_f32_e32 v235, v235
	v_exp_f32_e32 v236, v236
	v_exp_f32_e32 v237, v237
	v_exp_f32_e32 v238, v238
	v_exp_f32_e32 v239, v239
	v_exp_f32_e32 v240, v240
	v_exp_f32_e32 v241, v241
	v_mul_f32_e32 v226, v226, v225
	v_mul_f32_e32 v227, v227, v225
	v_mul_f32_e32 v228, v228, v225
	v_mul_f32_e32 v229, v229, v225
	v_mul_f32_e32 v230, v230, v225
	v_mul_f32_e32 v231, v231, v225
	v_mul_f32_e32 v232, v232, v225
	v_mul_f32_e32 v233, v233, v225
	v_add_f32_e32 v234, 1.0, v234
	v_add_f32_e32 v235, 1.0, v235
	v_add_f32_e32 v236, 1.0, v236
	v_add_f32_e32 v237, 1.0, v237
	v_add_f32_e32 v238, 1.0, v238
	v_add_f32_e32 v239, 1.0, v239
	v_add_f32_e32 v240, 1.0, v240
	v_add_f32_e32 v241, 1.0, v241
	v_rcp_f32_e32 v234, v234
	v_rcp_f32_e32 v235, v235
	v_rcp_f32_e32 v236, v236
	v_rcp_f32_e32 v237, v237
	v_rcp_f32_e32 v238, v238
	v_rcp_f32_e32 v239, v239
	v_rcp_f32_e32 v240, v240
	v_rcp_f32_e32 v241, v241
	v_mul_f32_e32 v226, v226, v234
	v_mul_f32_e32 v227, v227, v235
	v_mul_f32_e32 v228, v228, v236
	v_mul_f32_e32 v229, v229, v237
	v_mul_f32_e32 v230, v230, v238
	v_mul_f32_e32 v231, v231, v239
	v_mul_f32_e32 v232, v232, v240
	v_mul_f32_e32 v233, v233, v241
	v_cvt_pk_bf16_f32 v246, v226, v227
	v_cvt_pk_bf16_f32 v247, v228, v229
	v_cvt_pk_bf16_f32 v248, v230, v231
	v_cvt_pk_bf16_f32 v249, v232, v233
	v_lshlrev_b32_e32 v55, 2, v67
	v_and_b32_e32 v55, 32, v55
; __host__ __device__ __forceinline__ size_t tiled_off(int row, int col, int K) { return ((size_t)(row >> 7) * (K >> 6) + (col >> 6)) * 8192 + (lds_byte(row & 127, col & 63) >> 1); }
; __device__ __forceinline__ unsigned cvt_pk_bf16(float lo, float hi) { unsigned r; asm volatile("v_cvt_pk_bf16_f32 %0, %1, %2" : "=v"(r) : "v"(lo), "v"(hi)); return r; }
; __device__ __forceinline__ float fast_sigmoid(float x) { return __builtin_amdgcn_rcpf(1.0f + __builtin_amdgcn_exp2f(x * -1.4426950408889634f)); }
;     __device__ __forceinline__ void operator()(const f32x4 (&acc)[2][2][4][2], const Unit& u, int wr, int wc, int fr, int fq, const PG8_LAS float* rtab) const {
;     ...
;             for (int m = 0; m < 4; ++m) { const float r = rs[ai][m]; float o[8];
; #pragma unroll
;                 for (int n = 0; n < 2; ++n) { const f32x4 a = acc[ai][0][m][n] * r + bv[n], g = acc[ai][1][m][n] * r + bg[n];
; #pragma unroll
;                     for (int e = 0; e < 4; ++e) o[4 * n + e] = (MODE == 0) ? a[e] * fast_sigmoid(g[e]) : a[e] * fast_sigmoid(a[e]) * g[e]; }
;                 u32x4 w; w.x = cvt_pk_bf16(o[0], o[1]); w.y = cvt_pk_bf16(o[2], o[3]); w.z = cvt_pk_bf16(o[4], o[5]); w.w = cvt_pk_bf16(o[6], o[7]);
;                 if (MODE == 1) *(u32x4*)(O + tiled_off(row0 + ai * HALF + m * 16, lcol, ldc)) = w;
;                 else *(u32x4*)(O + (size_t)(row0 + ai * HALF + m * 16) * ldc + lcol) = w; }
	v_lshlrev_b32_e32 v54, 6, v67
	v_and_or_b32 v54, v54, s40, v143
	v_bitop3_b32 v130, v54, s42, v55 bitop3:0xde
	v_mul_lo_u32 v48, v66, 44
	v_ashrrev_i32_e32 v49, 31, v48
	v_lshl_add_u64 v[48:49], v[48:49], 0, s[60:61]
	v_lshlrev_b64 v[48:49], 14, v[48:49]
	v_lshl_add_u64 v[48:49], s[14:15], 0, v[48:49]
	v_lshl_add_u64 v[56:57], v[48:49], 0, v[130:131]
	global_store_dwordx4 v[56:57], v[246:249], off
	s_nop 0
	v_mul_f32_e32 v224, 0xbfb8aa3b, v139
	v_mul_f32_e32 v225, v139, v139
	v_mul_f32_e32 v234, v44, v224
	v_mul_f32_e32 v235, v45, v224
	v_mul_f32_e32 v236, v46, v224
	v_mul_f32_e32 v237, v47, v224
	v_mul_f32_e32 v238, v36, v224
	v_mul_f32_e32 v239, v37, v224
	v_mul_f32_e32 v240, v38, v224
	v_mul_f32_e32 v241, v39, v224
	v_mul_f32_e32 v226, v44, v40
	v_mul_f32_e32 v227, v45, v41
	v_mul_f32_e32 v228, v46, v42
	v_mul_f32_e32 v229, v47, v43
	v_mul_f32_e32 v230, v36, v32
	v_mul_f32_e32 v231, v37, v33
	v_mul_f32_e32 v232, v38, v34
	v_mul_f32_e32 v233, v39, v35
	v_exp_f32_e32 v234, v234
	v_exp_f32_e32 v235, v235
	v_exp_f32_e32 v236, v236
	v_exp_f32_e32 v237, v237
	v_exp_f32_e32 v238, v238
	v_exp_f32_e32 v239, v239
	v_exp_f32_e32 v240, v240
	v_exp_f32_e32 v241, v241
	v_mul_f32_e32 v226, v226, v225
	v_mul_f32_e32 v227, v227, v225
	v_mul_f32_e32 v228, v228, v225
	v_mul_f32_e32 v229, v229, v225
	v_mul_f32_e32 v230, v230, v225
	v_mul_f32_e32 v231, v231, v225
	v_mul_f32_e32 v232, v232, v225
	v_mul_f32_e32 v233, v233, v225
	v_add_f32_e32 v234, 1.0, v234
	v_add_f32_e32 v235, 1.0, v235
	v_add_f32_e32 v236, 1.0, v236
	v_add_f32_e32 v237, 1.0, v237
	v_add_f32_e32 v238, 1.0, v238
	v_add_f32_e32 v239, 1.0, v239
	v_add_f32_e32 v240, 1.0, v240
	v_add_f32_e32 v241, 1.0, v241
	v_rcp_f32_e32 v234, v234
	v_rcp_f32_e32 v235, v235
	v_rcp_f32_e32 v236, v236
	v_rcp_f32_e32 v237, v237
	v_rcp_f32_e32 v238, v238
	v_rcp_f32_e32 v239, v239
	v_rcp_f32_e32 v240, v240
	v_rcp_f32_e32 v241, v241
	v_mul_f32_e32 v226, v226, v234
	v_mul_f32_e32 v227, v227, v235
	v_mul_f32_e32 v228, v228, v236
	v_mul_f32_e32 v229, v229, v237
	v_mul_f32_e32 v230, v230, v238
	v_mul_f32_e32 v231, v231, v239
	v_mul_f32_e32 v232, v232, v240
	v_mul_f32_e32 v233, v233, v241
	v_cvt_pk_bf16_f32 v250, v226, v227
	v_cvt_pk_bf16_f32 v251, v228, v229
	v_cvt_pk_bf16_f32 v252, v230, v231
	v_cvt_pk_bf16_f32 v253, v232, v233
	v_add_u32_e32 v36, 0x90, v151
	v_lshrrev_b32_e32 v37, 3, v36
	v_and_or_b32 v37, v37, 10, s41
	v_lshlrev_b32_e32 v38, 6, v36
	v_lshlrev_b32_e32 v36, 2, v36
	v_and_or_b32 v38, v38, s40, v143
	v_lshlrev_b32_e32 v37, 10, v37
	v_and_b32_e32 v36, 32, v36
	v_bitop3_b32 v130, v38, v37, v36 bitop3:0xde
	v_mul_f32_e32 v224, 0xbfb8aa3b, v136
	v_mul_f32_e32 v225, v136, v136
	v_mul_f32_e32 v234, v28, v224
	v_mul_f32_e32 v235, v29, v224
	v_mul_f32_e32 v236, v30, v224
	v_mul_f32_e32 v237, v31, v224
	v_mul_f32_e32 v238, v20, v224
	v_mul_f32_e32 v239, v21, v224
	v_mul_f32_e32 v240, v22, v224
	v_mul_f32_e32 v241, v23, v224
	v_mul_f32_e32 v226, v28, v24
	v_mul_f32_e32 v227, v29, v25
	v_mul_f32_e32 v228, v30, v26
	v_mul_f32_e32 v229, v31, v27
	v_mul_f32_e32 v230, v20, v16
	v_mul_f32_e32 v231, v21, v17
	v_mul_f32_e32 v232, v22, v18
	v_mul_f32_e32 v233, v23, v19
	v_exp_f32_e32 v234, v234
	v_exp_f32_e32 v235, v235
	v_exp_f32_e32 v236, v236
	v_exp_f32_e32 v237, v237
	v_exp_f32_e32 v238, v238
	v_exp_f32_e32 v239, v239
	v_exp_f32_e32 v240, v240
	v_exp_f32_e32 v241, v241
	v_mul_f32_e32 v226, v226, v225
	v_mul_f32_e32 v227, v227, v225
	v_mul_f32_e32 v228, v228, v225
	v_mul_f32_e32 v229, v229, v225
	v_mul_f32_e32 v230, v230, v225
	v_mul_f32_e32 v231, v231, v225
	v_mul_f32_e32 v232, v232, v225
	v_mul_f32_e32 v233, v233, v225
	v_add_f32_e32 v234, 1.0, v234
	v_add_f32_e32 v235, 1.0, v235
	v_add_f32_e32 v236, 1.0, v236
	v_add_f32_e32 v237, 1.0, v237
	v_add_f32_e32 v238, 1.0, v238
	v_add_f32_e32 v239, 1.0, v239
	v_add_f32_e32 v240, 1.0, v240
	v_add_f32_e32 v241, 1.0, v241
	v_rcp_f32_e32 v234, v234
	v_rcp_f32_e32 v235, v235
	v_rcp_f32_e32 v236, v236
	v_rcp_f32_e32 v237, v237
	v_rcp_f32_e32 v238, v238
	v_rcp_f32_e32 v239, v239
	v_rcp_f32_e32 v240, v240
	v_rcp_f32_e32 v241, v241
	v_mul_f32_e32 v226, v226, v234
; __host__ __device__ __forceinline__ size_t tiled_off(int row, int col, int K) { return ((size_t)(row >> 7) * (K >> 6) + (col >> 6)) * 8192 + (lds_byte(row & 127, col & 63) >> 1); }
; __device__ __forceinline__ unsigned cvt_pk_bf16(float lo, float hi) { unsigned r; asm volatile("v_cvt_pk_bf16_f32 %0, %1, %2" : "=v"(r) : "v"(lo), "v"(hi)); return r; }
; __device__ __forceinline__ float fast_sigmoid(float x) { return __builtin_amdgcn_rcpf(1.0f + __builtin_amdgcn_exp2f(x * -1.4426950408889634f)); }
;     __device__ __forceinline__ void operator()(const f32x4 (&acc)[2][2][4][2], const Unit& u, int wr, int wc, int fr, int fq, const PG8_LAS float* rtab) const {
;     ...
;             for (int m = 0; m < 4; ++m) { const float r = rs[ai][m]; float o[8];
; #pragma unroll
;                 for (int n = 0; n < 2; ++n) { const f32x4 a = acc[ai][0][m][n] * r + bv[n], g = acc[ai][1][m][n] * r + bg[n];
; #pragma unroll
;                     for (int e = 0; e < 4; ++e) o[4 * n + e] = (MODE == 0) ? a[e] * fast_sigmoid(g[e]) : a[e] * fast_sigmoid(a[e]) * g[e]; }
;                 u32x4 w; w.x = cvt_pk_bf16(o[0], o[1]); w.y = cvt_pk_bf16(o[2], o[3]); w.z = cvt_pk_bf16(o[4], o[5]); w.w = cvt_pk_bf16(o[6], o[7]);
;                 if (MODE == 1) *(u32x4*)(O + tiled_off(row0 + ai * HALF + m * 16, lcol, ldc)) = w;
;                 else *(u32x4*)(O + (size_t)(row0 + ai * HALF + m * 16) * ldc + lcol) = w; }
	v_mul_f32_e32 v227, v227, v235
	v_mul_f32_e32 v228, v228, v236
	v_mul_f32_e32 v229, v229, v237
	v_mul_f32_e32 v230, v230, v238
	v_mul_f32_e32 v231, v231, v239
	v_mul_f32_e32 v232, v232, v240
	v_mul_f32_e32 v233, v233, v241
	v_cvt_pk_bf16_f32 v242, v226, v227
	v_cvt_pk_bf16_f32 v243, v228, v229
	v_cvt_pk_bf16_f32 v244, v230, v231
	v_cvt_pk_bf16_f32 v245, v232, v233
	v_lshl_add_u64 v[28:29], v[48:49], 0, v[130:131]
	global_store_dwordx4 v[28:29], v[250:253], off
	v_add_u32_e32 v20, 0xa0, v151
	v_lshrrev_b32_e32 v21, 3, v20
	v_and_or_b32 v21, v21, 12, s41
	v_lshlrev_b32_e32 v22, 6, v20
	v_lshlrev_b32_e32 v20, 2, v20
	v_and_or_b32 v22, v22, s40, v143
	v_lshlrev_b32_e32 v21, 10, v21
	v_and_b32_e32 v20, 32, v20
	v_bitop3_b32 v130, v22, v21, v20 bitop3:0xde
	v_lshl_add_u64 v[22:23], v[48:49], 0, v[130:131]
	global_store_dwordx4 v[22:23], v[242:245], off
	v_mul_f32_e32 v224, 0xbfb8aa3b, v137
	v_mul_f32_e32 v225, v137, v137
	v_mul_f32_e32 v234, v12, v224
	v_mul_f32_e32 v235, v13, v224
	v_mul_f32_e32 v236, v14, v224
	v_mul_f32_e32 v237, v15, v224
	v_mul_f32_e32 v238, v4, v224
	v_mul_f32_e32 v239, v5, v224
	v_mul_f32_e32 v240, v6, v224
	v_mul_f32_e32 v241, v7, v224
	v_mul_f32_e32 v226, v12, v8
	v_mul_f32_e32 v227, v13, v9
	v_mul_f32_e32 v228, v14, v10
	v_mul_f32_e32 v229, v15, v11
	v_mul_f32_e32 v230, v4, v0
	v_mul_f32_e32 v231, v5, v1
	v_mul_f32_e32 v232, v6, v2
	v_mul_f32_e32 v233, v7, v3
	v_exp_f32_e32 v234, v234
	v_exp_f32_e32 v235, v235
	v_exp_f32_e32 v236, v236
	v_exp_f32_e32 v237, v237
	v_exp_f32_e32 v238, v238
	v_exp_f32_e32 v239, v239
	v_exp_f32_e32 v240, v240
	v_exp_f32_e32 v241, v241
	v_mul_f32_e32 v226, v226, v225
	v_mul_f32_e32 v227, v227, v225
	v_mul_f32_e32 v228, v228, v225
	v_mul_f32_e32 v229, v229, v225
	v_mul_f32_e32 v230, v230, v225
	v_mul_f32_e32 v231, v231, v225
	v_mul_f32_e32 v232, v232, v225
	v_mul_f32_e32 v233, v233, v225
	v_add_f32_e32 v234, 1.0, v234
	v_add_f32_e32 v235, 1.0, v235
	v_add_f32_e32 v236, 1.0, v236
	v_add_f32_e32 v237, 1.0, v237
	v_add_f32_e32 v238, 1.0, v238
	v_add_f32_e32 v239, 1.0, v239
	v_add_f32_e32 v240, 1.0, v240
	v_add_f32_e32 v241, 1.0, v241
	v_rcp_f32_e32 v234, v234
	v_rcp_f32_e32 v235, v235
	v_rcp_f32_e32 v236, v236
	v_rcp_f32_e32 v237, v237
	v_rcp_f32_e32 v238, v238
	v_rcp_f32_e32 v239, v239
	v_rcp_f32_e32 v240, v240
	v_rcp_f32_e32 v241, v241
	v_mul_f32_e32 v226, v226, v234
	v_mul_f32_e32 v227, v227, v235
	v_mul_f32_e32 v228, v228, v236
	v_mul_f32_e32 v229, v229, v237
	v_mul_f32_e32 v230, v230, v238
	v_mul_f32_e32 v231, v231, v239
	v_mul_f32_e32 v232, v232, v240
	v_mul_f32_e32 v233, v233, v241
	v_cvt_pk_bf16_f32 v246, v226, v227
	v_cvt_pk_bf16_f32 v247, v228, v229
	v_cvt_pk_bf16_f32 v248, v230, v231
	v_cvt_pk_bf16_f32 v249, v232, v233
	v_add_u32_e32 v4, 0xb0, v151
	v_lshrrev_b32_e32 v5, 3, v4
	v_and_or_b32 v5, v5, 14, s41
	v_lshlrev_b32_e32 v6, 6, v4
	v_lshlrev_b32_e32 v4, 2, v4
	v_and_or_b32 v6, v6, s40, v143
	v_lshlrev_b32_e32 v5, 10, v5
	v_and_b32_e32 v4, 32, v4
	v_bitop3_b32 v130, v6, v5, v4 bitop3:0xde
	v_lshl_add_u64 v[4:5], v[48:49], 0, v[130:131]
	global_store_dwordx4 v[4:5], v[246:249], off
	s_cbranch_vccnz .LBB0_786
	s_and_saveexec_b64 s[4:5], s[2:3]
	s_cbranch_execz .LBB0_796
	v_lshl_or_b32 v0, s54, 8, v208
	v_ashrrev_i32_e32 v1, 31, v0
	v_lshlrev_b64 v[0:1], 6, v[0:1]
	v_lshl_add_u64 v[12:13], s[24:25], 0, v[0:1]
	global_load_dwordx4 v[0:3], v[12:13], off
	global_load_dwordx4 v[4:7], v[12:13], off offset:16
	global_load_dwordx4 v[8:11], v[12:13], off offset:32
	s_nop 0
	global_load_dwordx4 v[12:15], v[12:13], off offset:48
	s_lshl_b32 s53, s78, 10
	s_and_b32 s53, s53, 0x400
	s_waitcnt vmcnt(0)
	v_pk_add_f32 v[2:3], v[2:3], v[6:7]
	v_pk_add_f32 v[0:1], v[0:1], v[4:5]
	v_pk_add_f32 v[4:5], v[10:11], v[14:15]
	v_pk_add_f32 v[6:7], v[8:9], v[12:13]
	v_pk_add_f32 v[2:3], v[2:3], v[4:5]
	v_pk_add_f32 v[0:1], v[0:1], v[6:7]
	s_nop 0
	v_pk_mov_b32 v[4:5], v[0:1], v[2:3] op_sel:[1,0]
	v_mov_b32_e32 v1, v3
	v_pk_add_f32 v[0:1], v[4:5], v[0:1]
	s_nop 0
	v_add_f32_e32 v0, v0, v1
	v_fmamk_f32 v0, v0, 0x3a800000, v150
	v_rsq_f32_e32 v0, v0
	v_add_u32_e32 v1, s53, v145
	ds_write_b32 v1, v0

; #define PG8_LAS __attribute__((address_space(3)))
; __host__ __device__ __forceinline__ size_t tiled_off(int row, int col, int K) { return ((size_t)(row >> 7) * (K >> 6) + (col >> 6)) * 8192 + (lds_byte(row & 127, col & 63) >> 1); }
; __device__ __forceinline__ unsigned cvt_pk_bf16(float lo, float hi) { unsigned r; asm volatile("v_cvt_pk_bf16_f32 %0, %1, %2" : "=v"(r) : "v"(lo), "v"(hi)); return r; }
; __device__ __forceinline__ float fast_sigmoid(float x) { return __builtin_amdgcn_rcpf(1.0f + __builtin_amdgcn_exp2f(x * -1.4426950408889634f)); }
;     __device__ __forceinline__ void operator()(const f32x4 (&acc)[2][2][4][2], const Unit& u, int wr, int wc, int fr, int fq, const PG8_LAS float* rtab) const {
;         const int row0 = u.pm * BM + wr * 64 + fr, lcol = u.pn * HALF + wc * 32 + 8 * fq;
;         float rs[2][4]; load_rstd(rtab, wr, fr, rs);
;         f32x4 bv[2], bg[2];
; #pragma unroll
;         for (int n = 0; n < 2; ++n) { bv[n] = (MODE == 0) ? *(const f32x4*)(b0 + lcol + 4 * n) : (f32x4){0.f, 0.f, 0.f, 0.f}; bg[n] = (MODE == 0) ? *(const f32x4*)(b1 + lcol + 4 * n) : (f32x4){0.f, 0.f, 0.f, 0.f}; }
; #pragma unroll
;         for (int ai = 0; ai < 2; ++ai)
; #pragma unroll
;             for (int m = 0; m < 4; ++m) { const float r = rs[ai][m]; float o[8];
; #pragma unroll
;                 for (int n = 0; n < 2; ++n) { const f32x4 a = acc[ai][0][m][n] * r + bv[n], g = acc[ai][1][m][n] * r + bg[n];
; #pragma unroll
;                     for (int e = 0; e < 4; ++e) o[4 * n + e] = (MODE == 0) ? a[e] * fast_sigmoid(g[e]) : a[e] * fast_sigmoid(a[e]) * g[e]; }
;                 u32x4 w; w.x = cvt_pk_bf16(o[0], o[1]); w.y = cvt_pk_bf16(o[2], o[3]); w.z = cvt_pk_bf16(o[4], o[5]); w.w = cvt_pk_bf16(o[6], o[7]);
;                 if (MODE == 1) *(u32x4*)(O + tiled_off(row0 + ai * HALF + m * 16, lcol, ldc)) = w;
;                 else *(u32x4*)(O + (size_t)(row0 + ai * HALF + m * 16) * ldc + lcol) = w; }
; template <class Epi, class Sched, bool ALIGN_EPI = false, bool SP2 = false, bool TA = true>
; __device__ __forceinline__ void gemm_phase(PG8_LAS unsigned char* lds, const Gemm g, const Sched& S, const Epi& E) {
;     ...
;         if constexpr (ALIGN_EPI) { if (wr == 0) PG8_BAR; }
;         if constexpr (!Epi::AFTER_DRAIN) { E(acc, cur, wr, wc, fr, fq, (const PG8_LAS float*)(lds + STAGE_BYTES + 1024 + (ui & 1) * 1024)); S.done(cur); }
.LBB0_1628:
	s_lshl_b32 s45, s53, 10
	s_and_b32 s47, s45, 0x400
	v_add_u32_e32 v130, s47, v146
	ds_read2_b32 v[152:153], v130 offset1:16
	ds_read2_b32 v[140:141], v130 offset0:32 offset1:48
	ds_read2_b32 v[138:139], v130 offset0:128 offset1:144
	ds_read2_b32 v[136:137], v130 offset0:160 offset1:176
	s_waitcnt lgkmcnt(0)
	s_lshl_b32 s45, s52, 8
	s_add_i32 s45, s45, s62
	v_or_b32_e32 v151, s45, v142
	v_mul_f32_e32 v224, 0xbfb8aa3b, v152
	v_mul_f32_e32 v225, v152, v152
	v_mul_f32_e32 v234, v124, v224
	v_mul_f32_e32 v235, v125, v224
	v_mul_f32_e32 v236, v126, v224
	v_mul_f32_e32 v237, v127, v224
	v_mul_f32_e32 v238, v116, v224
	v_mul_f32_e32 v239, v117, v224
	v_mul_f32_e32 v240, v118, v224
	v_mul_f32_e32 v241, v119, v224
	v_mul_f32_e32 v226, v124, v120
	v_mul_f32_e32 v227, v125, v121
	v_mul_f32_e32 v228, v126, v122
	v_mul_f32_e32 v229, v127, v123
	v_mul_f32_e32 v230, v116, v112
	v_mul_f32_e32 v231, v117, v113
	v_mul_f32_e32 v232, v118, v114
	v_mul_f32_e32 v233, v119, v115
	v_exp_f32_e32 v234, v234
	v_exp_f32_e32 v235, v235
	v_exp_f32_e32 v236, v236
	v_exp_f32_e32 v237, v237
	v_exp_f32_e32 v238, v238
	v_exp_f32_e32 v239, v239
	v_exp_f32_e32 v240, v240
	v_exp_f32_e32 v241, v241
	v_mul_f32_e32 v226, v226, v225
	v_mul_f32_e32 v227, v227, v225
	v_mul_f32_e32 v228, v228, v225
	v_mul_f32_e32 v229, v229, v225
	v_mul_f32_e32 v230, v230, v225
	v_mul_f32_e32 v231, v231, v225
	v_mul_f32_e32 v232, v232, v225
	v_mul_f32_e32 v233, v233, v225
	v_add_f32_e32 v234, 1.0, v234
	v_add_f32_e32 v235, 1.0, v235
	v_add_f32_e32 v236, 1.0, v236
	v_add_f32_e32 v237, 1.0, v237
	v_add_f32_e32 v238, 1.0, v238
	v_add_f32_e32 v239, 1.0, v239
	v_add_f32_e32 v240, 1.0, v240
	v_add_f32_e32 v241, 1.0, v241
	v_rcp_f32_e32 v234, v234
	v_rcp_f32_e32 v235, v235
	v_rcp_f32_e32 v236, v236
	v_rcp_f32_e32 v237, v237
	v_rcp_f32_e32 v238, v238
	v_rcp_f32_e32 v239, v239
	v_rcp_f32_e32 v240, v240
	v_rcp_f32_e32 v241, v241
	v_mul_f32_e32 v226, v226, v234
	v_mul_f32_e32 v227, v227, v235
	v_mul_f32_e32 v228, v228, v236
	v_mul_f32_e32 v229, v229, v237
	v_mul_f32_e32 v230, v230, v238
	v_mul_f32_e32 v231, v231, v239
	v_mul_f32_e32 v232, v232, v240
	v_mul_f32_e32 v233, v233, v241
	v_cvt_pk_bf16_f32 v242, v226, v227
	v_cvt_pk_bf16_f32 v243, v228, v229
	v_cvt_pk_bf16_f32 v244, v230, v231
	v_cvt_pk_bf16_f32 v245, v232, v233
	v_lshlrev_b32_e32 v116, 6, v151
	v_and_or_b32 v118, v116, s64, v143
	v_lshlrev_b32_e32 v116, 2, v151
	v_and_b32_e32 v119, 32, v116
	s_lshl_b32 s47, s54, 7
	s_or_b32 s47, s47, s63
	s_ashr_i32 s52, s47, 6
	s_ashr_i32 s47, s45, 7
	s_mul_i32 s47, s47, 44
	s_ashr_i32 s53, s52, 31
	s_ashr_i32 s55, s47, 31
	s_add_u32 s54, s47, s52
	s_addc_u32 s55, s55, s53
	s_lshl_b64 s[54:55], s[54:55], 14
	s_add_u32 s54, s24, s54
	v_bitop3_b32 v120, v118, s66, v119 bitop3:0xde
	s_addc_u32 s55, s25, s55
	global_store_dwordx4 v120, v[242:245], s[54:55]
	s_or_b32 s47, s45, 16
	s_lshr_b32 s47, s47, 3
	s_and_b32 s47, s47, 10
	s_or_b32 s47, s47, s65
	s_lshl_b32 s47, s47, 10
	v_mul_f32_e32 v224, 0xbfb8aa3b, v140
	v_mul_f32_e32 v225, v140, v140
	v_mul_f32_e32 v234, v92, v224
	v_mul_f32_e32 v235, v93, v224
	v_mul_f32_e32 v236, v94, v224
	v_mul_f32_e32 v237, v95, v224
	v_mul_f32_e32 v238, v84, v224
	v_mul_f32_e32 v239, v85, v224
	v_mul_f32_e32 v240, v86, v224
	v_mul_f32_e32 v241, v87, v224
	v_mul_f32_e32 v226, v92, v88
	v_mul_f32_e32 v227, v93, v89
	v_mul_f32_e32 v228, v94, v90
	v_mul_f32_e32 v229, v95, v91
	v_mul_f32_e32 v230, v84, v80
	v_mul_f32_e32 v231, v85, v81
	v_mul_f32_e32 v232, v86, v82
	v_mul_f32_e32 v233, v87, v83
	v_exp_f32_e32 v234, v234
	v_exp_f32_e32 v235, v235
	v_exp_f32_e32 v236, v236
	v_exp_f32_e32 v237, v237
	v_exp_f32_e32 v238, v238
	v_exp_f32_e32 v239, v239
	v_exp_f32_e32 v240, v240
	v_exp_f32_e32 v241, v241
	v_mul_f32_e32 v226, v226, v225
	v_mul_f32_e32 v227, v227, v225
	v_mul_f32_e32 v228, v228, v225
	v_mul_f32_e32 v229, v229, v225
	v_mul_f32_e32 v230, v230, v225
	v_mul_f32_e32 v231, v231, v225
	v_mul_f32_e32 v232, v232, v225
	v_mul_f32_e32 v233, v233, v225
	v_add_f32_e32 v234, 1.0, v234
	v_add_f32_e32 v235, 1.0, v235
	v_add_f32_e32 v236, 1.0, v236
	v_add_f32_e32 v237, 1.0, v237
	v_add_f32_e32 v238, 1.0, v238
	v_add_f32_e32 v239, 1.0, v239
	v_add_f32_e32 v240, 1.0, v240
	v_add_f32_e32 v241, 1.0, v241
	v_rcp_f32_e32 v234, v234
	v_rcp_f32_e32 v235, v235
	v_rcp_f32_e32 v236, v236
	v_rcp_f32_e32 v237, v237
	v_rcp_f32_e32 v238, v238
	v_rcp_f32_e32 v239, v239
	v_rcp_f32_e32 v240, v240
	v_rcp_f32_e32 v241, v241
	v_mul_f32_e32 v226, v226, v234
	v_mul_f32_e32 v227, v227, v235
	v_mul_f32_e32 v228, v228, v236
	v_mul_f32_e32 v229, v229, v237
	v_mul_f32_e32 v230, v230, v238
	v_mul_f32_e32 v231, v231, v239
	v_mul_f32_e32 v232, v232, v240
	v_mul_f32_e32 v233, v233, v241
	v_cvt_pk_bf16_f32 v250, v226, v227
	v_cvt_pk_bf16_f32 v251, v228, v229
	v_cvt_pk_bf16_f32 v252, v230, v231
	v_cvt_pk_bf16_f32 v253, v232, v233
	v_bitop3_b32 v93, v118, s47, v119 bitop3:0xde
	v_mul_f32_e32 v224, 0xbfb8aa3b, v153
	v_mul_f32_e32 v225, v153, v153
	v_mul_f32_e32 v234, v108, v224
	v_mul_f32_e32 v235, v109, v224
	v_mul_f32_e32 v236, v110, v224
	v_mul_f32_e32 v237, v111, v224
	v_mul_f32_e32 v238, v100, v224
	v_mul_f32_e32 v239, v101, v224
	v_mul_f32_e32 v240, v102, v224
	v_mul_f32_e32 v241, v103, v224
	v_mul_f32_e32 v226, v108, v104
	v_mul_f32_e32 v227, v109, v105
	v_mul_f32_e32 v228, v110, v106
	v_mul_f32_e32 v229, v111, v107
	v_mul_f32_e32 v230, v100, v96
	v_mul_f32_e32 v231, v101, v97
	v_mul_f32_e32 v232, v102, v98
	v_mul_f32_e32 v233, v103, v99
	v_exp_f32_e32 v234, v234
	v_exp_f32_e32 v235, v235
	v_exp_f32_e32 v236, v236
	v_exp_f32_e32 v237, v237
	v_exp_f32_e32 v238, v238
	v_exp_f32_e32 v239, v239
	v_exp_f32_e32 v240, v240
; __host__ __device__ __forceinline__ size_t tiled_off(int row, int col, int K) { return ((size_t)(row >> 7) * (K >> 6) + (col >> 6)) * 8192 + (lds_byte(row & 127, col & 63) >> 1); }
; __device__ __forceinline__ unsigned cvt_pk_bf16(float lo, float hi) { unsigned r; asm volatile("v_cvt_pk_bf16_f32 %0, %1, %2" : "=v"(r) : "v"(lo), "v"(hi)); return r; }
; __device__ __forceinline__ float fast_sigmoid(float x) { return __builtin_amdgcn_rcpf(1.0f + __builtin_amdgcn_exp2f(x * -1.4426950408889634f)); }
; #define PG8_BAR __builtin_amdgcn_s_barrier()
;     __device__ __forceinline__ void operator()(const f32x4 (&acc)[2][2][4][2], const Unit& u, int wr, int wc, int fr, int fq, const PG8_LAS float* rtab) const {
;     ...
;             for (int m = 0; m < 4; ++m) { const float r = rs[ai][m]; float o[8];
; #pragma unroll
;                 for (int n = 0; n < 2; ++n) { const f32x4 a = acc[ai][0][m][n] * r + bv[n], g = acc[ai][1][m][n] * r + bg[n];
; #pragma unroll
;                     for (int e = 0; e < 4; ++e) o[4 * n + e] = (MODE == 0) ? a[e] * fast_sigmoid(g[e]) : a[e] * fast_sigmoid(a[e]) * g[e]; }
;                 u32x4 w; w.x = cvt_pk_bf16(o[0], o[1]); w.y = cvt_pk_bf16(o[2], o[3]); w.z = cvt_pk_bf16(o[4], o[5]); w.w = cvt_pk_bf16(o[6], o[7]);
;                 if (MODE == 1) *(u32x4*)(O + tiled_off(row0 + ai * HALF + m * 16, lcol, ldc)) = w;
;                 else *(u32x4*)(O + (size_t)(row0 + ai * HALF + m * 16) * ldc + lcol) = w; }
; template <class Epi, class Sched, bool ALIGN_EPI = false, bool SP2 = false, bool TA = true>
; __device__ __forceinline__ void gemm_phase(PG8_LAS unsigned char* lds, const Gemm g, const Sched& S, const Epi& E) {
;     ...
;         if constexpr (ALIGN_EPI) { if (wr == 0) PG8_BAR; }
	v_exp_f32_e32 v241, v241
	v_mul_f32_e32 v226, v226, v225
	v_mul_f32_e32 v227, v227, v225
	v_mul_f32_e32 v228, v228, v225
	v_mul_f32_e32 v229, v229, v225
	v_mul_f32_e32 v230, v230, v225
	v_mul_f32_e32 v231, v231, v225
	v_mul_f32_e32 v232, v232, v225
	v_mul_f32_e32 v233, v233, v225
	v_add_f32_e32 v234, 1.0, v234
	v_add_f32_e32 v235, 1.0, v235
	v_add_f32_e32 v236, 1.0, v236
	v_add_f32_e32 v237, 1.0, v237
	v_add_f32_e32 v238, 1.0, v238
	v_add_f32_e32 v239, 1.0, v239
	v_add_f32_e32 v240, 1.0, v240
	v_add_f32_e32 v241, 1.0, v241
	v_rcp_f32_e32 v234, v234
	v_rcp_f32_e32 v235, v235
	v_rcp_f32_e32 v236, v236
	v_rcp_f32_e32 v237, v237
	v_rcp_f32_e32 v238, v238
	v_rcp_f32_e32 v239, v239
	v_rcp_f32_e32 v240, v240
	v_rcp_f32_e32 v241, v241
	v_mul_f32_e32 v226, v226, v234
	v_mul_f32_e32 v227, v227, v235
	v_mul_f32_e32 v228, v228, v236
	v_mul_f32_e32 v229, v229, v237
	v_mul_f32_e32 v230, v230, v238
	v_mul_f32_e32 v231, v231, v239
	v_mul_f32_e32 v232, v232, v240
	v_mul_f32_e32 v233, v233, v241
	v_cvt_pk_bf16_f32 v246, v226, v227
	v_cvt_pk_bf16_f32 v247, v228, v229
	v_cvt_pk_bf16_f32 v248, v230, v231
	v_cvt_pk_bf16_f32 v249, v232, v233
	global_store_dwordx4 v93, v[246:249], s[54:55]
	s_or_b32 s47, s45, 32
	s_lshr_b32 s47, s47, 3
	s_and_b32 s47, s47, 12
	s_or_b32 s47, s47, s65
	s_lshl_b32 s47, s47, 10
	v_bitop3_b32 v87, v118, s47, v119 bitop3:0xde
	global_store_dwordx4 v87, v[250:253], s[54:55]
	s_or_b32 s45, s45, 48
	s_lshr_b32 s45, s45, 3
	s_and_b32 s45, s45, 14
	s_or_b32 s45, s45, s65
	s_lshl_b32 s45, s45, 10
	v_mul_f32_e32 v224, 0xbfb8aa3b, v141
	v_mul_f32_e32 v225, v141, v141
	v_mul_f32_e32 v234, v76, v224
	v_mul_f32_e32 v235, v77, v224
	v_mul_f32_e32 v236, v78, v224
	v_mul_f32_e32 v237, v79, v224
	v_mul_f32_e32 v238, v68, v224
	v_mul_f32_e32 v239, v69, v224
	v_mul_f32_e32 v240, v70, v224
	v_mul_f32_e32 v241, v71, v224
	v_mul_f32_e32 v226, v76, v72
	v_mul_f32_e32 v227, v77, v73
	v_mul_f32_e32 v228, v78, v74
	v_mul_f32_e32 v229, v79, v75
	v_mul_f32_e32 v230, v68, v64
	v_mul_f32_e32 v231, v69, v65
	v_mul_f32_e32 v232, v70, v66
	v_mul_f32_e32 v233, v71, v67
	v_exp_f32_e32 v234, v234
	v_exp_f32_e32 v235, v235
	v_exp_f32_e32 v236, v236
	v_exp_f32_e32 v237, v237
	v_exp_f32_e32 v238, v238
	v_exp_f32_e32 v239, v239
	v_exp_f32_e32 v240, v240
	v_exp_f32_e32 v241, v241
	v_mul_f32_e32 v226, v226, v225
	v_mul_f32_e32 v227, v227, v225
	v_mul_f32_e32 v228, v228, v225
	v_mul_f32_e32 v229, v229, v225
	v_mul_f32_e32 v230, v230, v225
	v_mul_f32_e32 v231, v231, v225
	v_mul_f32_e32 v232, v232, v225
	v_mul_f32_e32 v233, v233, v225
	v_add_f32_e32 v234, 1.0, v234
	v_add_f32_e32 v235, 1.0, v235
	v_add_f32_e32 v236, 1.0, v236
	v_add_f32_e32 v237, 1.0, v237
	v_add_f32_e32 v238, 1.0, v238
	v_add_f32_e32 v239, 1.0, v239
	v_add_f32_e32 v240, 1.0, v240
	v_add_f32_e32 v241, 1.0, v241
	v_rcp_f32_e32 v234, v234
	v_rcp_f32_e32 v235, v235
	v_rcp_f32_e32 v236, v236
	v_rcp_f32_e32 v237, v237
	v_rcp_f32_e32 v238, v238
	v_rcp_f32_e32 v239, v239
	v_rcp_f32_e32 v240, v240
	v_rcp_f32_e32 v241, v241
	v_mul_f32_e32 v226, v226, v234
	v_mul_f32_e32 v227, v227, v235
	v_mul_f32_e32 v228, v228, v236
	v_mul_f32_e32 v229, v229, v237
	v_mul_f32_e32 v230, v230, v238
	v_mul_f32_e32 v231, v231, v239
	v_mul_f32_e32 v232, v232, v240
	v_mul_f32_e32 v233, v233, v241
	v_cvt_pk_bf16_f32 v242, v226, v227
	v_cvt_pk_bf16_f32 v243, v228, v229
	v_cvt_pk_bf16_f32 v244, v230, v231
	v_cvt_pk_bf16_f32 v245, v232, v233
	v_bitop3_b32 v68, v118, s45, v119 bitop3:0xde
	global_store_dwordx4 v68, v[242:245], s[54:55]
	s_and_b64 vcc, exec, s[42:43]
	s_cbranch_vccz .Lalign_up1
	s_barrier
.Lalign_up1:
	s_andn2_b64 vcc, exec, s[4:5]
	s_mov_b64 s[4:5], -1
	v_add_u32_e32 v67, 0x80, v151
	v_ashrrev_i32_e32 v66, 7, v67
	v_mul_f32_e32 v224, 0xbfb8aa3b, v138
	v_mul_f32_e32 v225, v138, v138
	v_mul_f32_e32 v234, v60, v224
	v_mul_f32_e32 v235, v61, v224
	v_mul_f32_e32 v236, v62, v224
	v_mul_f32_e32 v237, v63, v224
	v_mul_f32_e32 v238, v52, v224
	v_mul_f32_e32 v239, v53, v224
	v_mul_f32_e32 v240, v54, v224
	v_mul_f32_e32 v241, v55, v224
	v_mul_f32_e32 v226, v60, v56
	v_mul_f32_e32 v227, v61, v57
	v_mul_f32_e32 v228, v62, v58
	v_mul_f32_e32 v229, v63, v59
	v_mul_f32_e32 v230, v52, v48
	v_mul_f32_e32 v231, v53, v49
	v_mul_f32_e32 v232, v54, v50
	v_mul_f32_e32 v233, v55, v51
	v_exp_f32_e32 v234, v234
	v_exp_f32_e32 v235, v235
	v_exp_f32_e32 v236, v236
	v_exp_f32_e32 v237, v237
	v_exp_f32_e32 v238, v238
	v_exp_f32_e32 v239, v239
	v_exp_f32_e32 v240, v240
	v_exp_f32_e32 v241, v241
	v_mul_f32_e32 v226, v226, v225
	v_mul_f32_e32 v227, v227, v225
	v_mul_f32_e32 v228, v228, v225
	v_mul_f32_e32 v229, v229, v225
	v_mul_f32_e32 v230, v230, v225
	v_mul_f32_e32 v231, v231, v225
	v_mul_f32_e32 v232, v232, v225
	v_mul_f32_e32 v233, v233, v225
	v_add_f32_e32 v234, 1.0, v234
	v_add_f32_e32 v235, 1.0, v235
	v_add_f32_e32 v236, 1.0, v236
	v_add_f32_e32 v237, 1.0, v237
	v_add_f32_e32 v238, 1.0, v238
	v_add_f32_e32 v239, 1.0, v239
	v_add_f32_e32 v240, 1.0, v240
	v_add_f32_e32 v241, 1.0, v241
	v_rcp_f32_e32 v234, v234
	v_rcp_f32_e32 v235, v235
	v_rcp_f32_e32 v236, v236
	v_rcp_f32_e32 v237, v237
	v_rcp_f32_e32 v238, v238
	v_rcp_f32_e32 v239, v239
	v_rcp_f32_e32 v240, v240
	v_rcp_f32_e32 v241, v241
	v_mul_f32_e32 v226, v226, v234
	v_mul_f32_e32 v227, v227, v235
	v_mul_f32_e32 v228, v228, v236
	v_mul_f32_e32 v229, v229, v237
	v_mul_f32_e32 v230, v230, v238
	v_mul_f32_e32 v231, v231, v239
	v_mul_f32_e32 v232, v232, v240
	v_mul_f32_e32 v233, v233, v241
	v_cvt_pk_bf16_f32 v246, v226, v227
	v_cvt_pk_bf16_f32 v247, v228, v229
	v_cvt_pk_bf16_f32 v248, v230, v231
	v_cvt_pk_bf16_f32 v249, v232, v233
	v_lshlrev_b32_e32 v55, 2, v67
	v_and_b32_e32 v55, 32, v55
; __host__ __device__ __forceinline__ size_t tiled_off(int row, int col, int K) { return ((size_t)(row >> 7) * (K >> 6) + (col >> 6)) * 8192 + (lds_byte(row & 127, col & 63) >> 1); }
; __device__ __forceinline__ unsigned cvt_pk_bf16(float lo, float hi) { unsigned r; asm volatile("v_cvt_pk_bf16_f32 %0, %1, %2" : "=v"(r) : "v"(lo), "v"(hi)); return r; }
; __device__ __forceinline__ float fast_sigmoid(float x) { return __builtin_amdgcn_rcpf(1.0f + __builtin_amdgcn_exp2f(x * -1.4426950408889634f)); }
;     __device__ __forceinline__ void operator()(const f32x4 (&acc)[2][2][4][2], const Unit& u, int wr, int wc, int fr, int fq, const PG8_LAS float* rtab) const {
;     ...
;             for (int m = 0; m < 4; ++m) { const float r = rs[ai][m]; float o[8];
; #pragma unroll
;                 for (int n = 0; n < 2; ++n) { const f32x4 a = acc[ai][0][m][n] * r + bv[n], g = acc[ai][1][m][n] * r + bg[n];
; #pragma unroll
;                     for (int e = 0; e < 4; ++e) o[4 * n + e] = (MODE == 0) ? a[e] * fast_sigmoid(g[e]) : a[e] * fast_sigmoid(a[e]) * g[e]; }
;                 u32x4 w; w.x = cvt_pk_bf16(o[0], o[1]); w.y = cvt_pk_bf16(o[2], o[3]); w.z = cvt_pk_bf16(o[4], o[5]); w.w = cvt_pk_bf16(o[6], o[7]);
;                 if (MODE == 1) *(u32x4*)(O + tiled_off(row0 + ai * HALF + m * 16, lcol, ldc)) = w;
;                 else *(u32x4*)(O + (size_t)(row0 + ai * HALF + m * 16) * ldc + lcol) = w; }
	v_lshlrev_b32_e32 v54, 6, v67
	v_and_or_b32 v54, v54, s64, v143
	v_bitop3_b32 v130, v54, s66, v55 bitop3:0xde
	v_mul_lo_u32 v48, v66, 44
	v_ashrrev_i32_e32 v49, 31, v48
	v_lshl_add_u64 v[48:49], v[48:49], 0, s[52:53]
	v_lshlrev_b64 v[48:49], 14, v[48:49]
	v_lshl_add_u64 v[48:49], s[24:25], 0, v[48:49]
	v_lshl_add_u64 v[56:57], v[48:49], 0, v[130:131]
	global_store_dwordx4 v[56:57], v[246:249], off
	s_nop 0
	v_mul_f32_e32 v224, 0xbfb8aa3b, v139
	v_mul_f32_e32 v225, v139, v139
	v_mul_f32_e32 v234, v44, v224
	v_mul_f32_e32 v235, v45, v224
	v_mul_f32_e32 v236, v46, v224
	v_mul_f32_e32 v237, v47, v224
	v_mul_f32_e32 v238, v36, v224
	v_mul_f32_e32 v239, v37, v224
	v_mul_f32_e32 v240, v38, v224
	v_mul_f32_e32 v241, v39, v224
	v_mul_f32_e32 v226, v44, v40
	v_mul_f32_e32 v227, v45, v41
	v_mul_f32_e32 v228, v46, v42
	v_mul_f32_e32 v229, v47, v43
	v_mul_f32_e32 v230, v36, v32
	v_mul_f32_e32 v231, v37, v33
	v_mul_f32_e32 v232, v38, v34
	v_mul_f32_e32 v233, v39, v35
	v_exp_f32_e32 v234, v234
	v_exp_f32_e32 v235, v235
	v_exp_f32_e32 v236, v236
	v_exp_f32_e32 v237, v237
	v_exp_f32_e32 v238, v238
	v_exp_f32_e32 v239, v239
	v_exp_f32_e32 v240, v240
	v_exp_f32_e32 v241, v241
	v_mul_f32_e32 v226, v226, v225
	v_mul_f32_e32 v227, v227, v225
	v_mul_f32_e32 v228, v228, v225
	v_mul_f32_e32 v229, v229, v225
	v_mul_f32_e32 v230, v230, v225
	v_mul_f32_e32 v231, v231, v225
	v_mul_f32_e32 v232, v232, v225
	v_mul_f32_e32 v233, v233, v225
	v_add_f32_e32 v234, 1.0, v234
	v_add_f32_e32 v235, 1.0, v235
	v_add_f32_e32 v236, 1.0, v236
	v_add_f32_e32 v237, 1.0, v237
	v_add_f32_e32 v238, 1.0, v238
	v_add_f32_e32 v239, 1.0, v239
	v_add_f32_e32 v240, 1.0, v240
	v_add_f32_e32 v241, 1.0, v241
	v_rcp_f32_e32 v234, v234
	v_rcp_f32_e32 v235, v235
	v_rcp_f32_e32 v236, v236
	v_rcp_f32_e32 v237, v237
	v_rcp_f32_e32 v238, v238
	v_rcp_f32_e32 v239, v239
	v_rcp_f32_e32 v240, v240
	v_rcp_f32_e32 v241, v241
	v_mul_f32_e32 v226, v226, v234
	v_mul_f32_e32 v227, v227, v235
	v_mul_f32_e32 v228, v228, v236
	v_mul_f32_e32 v229, v229, v237
	v_mul_f32_e32 v230, v230, v238
	v_mul_f32_e32 v231, v231, v239
	v_mul_f32_e32 v232, v232, v240
	v_mul_f32_e32 v233, v233, v241
	v_cvt_pk_bf16_f32 v250, v226, v227
	v_cvt_pk_bf16_f32 v251, v228, v229
	v_cvt_pk_bf16_f32 v252, v230, v231
	v_cvt_pk_bf16_f32 v253, v232, v233
	v_add_u32_e32 v36, 0x90, v151
	v_lshrrev_b32_e32 v37, 3, v36
	v_and_or_b32 v37, v37, 10, s65
	v_lshlrev_b32_e32 v38, 6, v36
	v_lshlrev_b32_e32 v36, 2, v36
	v_and_or_b32 v38, v38, s64, v143
	v_lshlrev_b32_e32 v37, 10, v37
	v_and_b32_e32 v36, 32, v36
	v_bitop3_b32 v130, v38, v37, v36 bitop3:0xde
	v_mul_f32_e32 v224, 0xbfb8aa3b, v136
	v_mul_f32_e32 v225, v136, v136
	v_mul_f32_e32 v234, v28, v224
	v_mul_f32_e32 v235, v29, v224
	v_mul_f32_e32 v236, v30, v224
	v_mul_f32_e32 v237, v31, v224
	v_mul_f32_e32 v238, v20, v224
	v_mul_f32_e32 v239, v21, v224
	v_mul_f32_e32 v240, v22, v224
	v_mul_f32_e32 v241, v23, v224
	v_mul_f32_e32 v226, v28, v24
	v_mul_f32_e32 v227, v29, v25
	v_mul_f32_e32 v228, v30, v26
	v_mul_f32_e32 v229, v31, v27
	v_mul_f32_e32 v230, v20, v16
	v_mul_f32_e32 v231, v21, v17
	v_mul_f32_e32 v232, v22, v18
	v_mul_f32_e32 v233, v23, v19
	v_exp_f32_e32 v234, v234
	v_exp_f32_e32 v235, v235
	v_exp_f32_e32 v236, v236
	v_exp_f32_e32 v237, v237
	v_exp_f32_e32 v238, v238
	v_exp_f32_e32 v239, v239
	v_exp_f32_e32 v240, v240
	v_exp_f32_e32 v241, v241
	v_mul_f32_e32 v226, v226, v225
	v_mul_f32_e32 v227, v227, v225
	v_mul_f32_e32 v228, v228, v225
	v_mul_f32_e32 v229, v229, v225
	v_mul_f32_e32 v230, v230, v225
	v_mul_f32_e32 v231, v231, v225
	v_mul_f32_e32 v232, v232, v225
	v_mul_f32_e32 v233, v233, v225
	v_add_f32_e32 v234, 1.0, v234
	v_add_f32_e32 v235, 1.0, v235
	v_add_f32_e32 v236, 1.0, v236
	v_add_f32_e32 v237, 1.0, v237
	v_add_f32_e32 v238, 1.0, v238
	v_add_f32_e32 v239, 1.0, v239
	v_add_f32_e32 v240, 1.0, v240
	v_add_f32_e32 v241, 1.0, v241
	v_rcp_f32_e32 v234, v234
	v_rcp_f32_e32 v235, v235
	v_rcp_f32_e32 v236, v236
	v_rcp_f32_e32 v237, v237
	v_rcp_f32_e32 v238, v238
	v_rcp_f32_e32 v239, v239
	v_rcp_f32_e32 v240, v240
	v_rcp_f32_e32 v241, v241
	v_mul_f32_e32 v226, v226, v234
; __host__ __device__ __forceinline__ size_t tiled_off(int row, int col, int K) { return ((size_t)(row >> 7) * (K >> 6) + (col >> 6)) * 8192 + (lds_byte(row & 127, col & 63) >> 1); }
; __device__ __forceinline__ unsigned cvt_pk_bf16(float lo, float hi) { unsigned r; asm volatile("v_cvt_pk_bf16_f32 %0, %1, %2" : "=v"(r) : "v"(lo), "v"(hi)); return r; }
; __device__ __forceinline__ float fast_sigmoid(float x) { return __builtin_amdgcn_rcpf(1.0f + __builtin_amdgcn_exp2f(x * -1.4426950408889634f)); }
;     __device__ __forceinline__ void operator()(const f32x4 (&acc)[2][2][4][2], const Unit& u, int wr, int wc, int fr, int fq, const PG8_LAS float* rtab) const {
;     ...
;             for (int m = 0; m < 4; ++m) { const float r = rs[ai][m]; float o[8];
; #pragma unroll
;                 for (int n = 0; n < 2; ++n) { const f32x4 a = acc[ai][0][m][n] * r + bv[n], g = acc[ai][1][m][n] * r + bg[n];
; #pragma unroll
;                     for (int e = 0; e < 4; ++e) o[4 * n + e] = (MODE == 0) ? a[e] * fast_sigmoid(g[e]) : a[e] * fast_sigmoid(a[e]) * g[e]; }
;                 u32x4 w; w.x = cvt_pk_bf16(o[0], o[1]); w.y = cvt_pk_bf16(o[2], o[3]); w.z = cvt_pk_bf16(o[4], o[5]); w.w = cvt_pk_bf16(o[6], o[7]);
;                 if (MODE == 1) *(u32x4*)(O + tiled_off(row0 + ai * HALF + m * 16, lcol, ldc)) = w;
;                 else *(u32x4*)(O + (size_t)(row0 + ai * HALF + m * 16) * ldc + lcol) = w; }
	v_mul_f32_e32 v227, v227, v235
	v_mul_f32_e32 v228, v228, v236
	v_mul_f32_e32 v229, v229, v237
	v_mul_f32_e32 v230, v230, v238
	v_mul_f32_e32 v231, v231, v239
	v_mul_f32_e32 v232, v232, v240
	v_mul_f32_e32 v233, v233, v241
	v_cvt_pk_bf16_f32 v242, v226, v227
	v_cvt_pk_bf16_f32 v243, v228, v229
	v_cvt_pk_bf16_f32 v244, v230, v231
	v_cvt_pk_bf16_f32 v245, v232, v233
	v_lshl_add_u64 v[28:29], v[48:49], 0, v[130:131]
	global_store_dwordx4 v[28:29], v[250:253], off
	v_add_u32_e32 v20, 0xa0, v151
	v_lshrrev_b32_e32 v21, 3, v20
	v_and_or_b32 v21, v21, 12, s65
	v_lshlrev_b32_e32 v22, 6, v20
	v_lshlrev_b32_e32 v20, 2, v20
	v_and_or_b32 v22, v22, s64, v143
	v_lshlrev_b32_e32 v21, 10, v21
	v_and_b32_e32 v20, 32, v20
	v_bitop3_b32 v130, v22, v21, v20 bitop3:0xde
	v_lshl_add_u64 v[22:23], v[48:49], 0, v[130:131]
	global_store_dwordx4 v[22:23], v[242:245], off
	v_mul_f32_e32 v224, 0xbfb8aa3b, v137
	v_mul_f32_e32 v225, v137, v137
	v_mul_f32_e32 v234, v12, v224
	v_mul_f32_e32 v235, v13, v224
	v_mul_f32_e32 v236, v14, v224
	v_mul_f32_e32 v237, v15, v224
	v_mul_f32_e32 v238, v4, v224
	v_mul_f32_e32 v239, v5, v224
	v_mul_f32_e32 v240, v6, v224
	v_mul_f32_e32 v241, v7, v224
	v_mul_f32_e32 v226, v12, v8
	v_mul_f32_e32 v227, v13, v9
	v_mul_f32_e32 v228, v14, v10
	v_mul_f32_e32 v229, v15, v11
	v_mul_f32_e32 v230, v4, v0
	v_mul_f32_e32 v231, v5, v1
	v_mul_f32_e32 v232, v6, v2
	v_mul_f32_e32 v233, v7, v3
	v_exp_f32_e32 v234, v234
	v_exp_f32_e32 v235, v235
	v_exp_f32_e32 v236, v236
	v_exp_f32_e32 v237, v237
	v_exp_f32_e32 v238, v238
	v_exp_f32_e32 v239, v239
	v_exp_f32_e32 v240, v240
	v_exp_f32_e32 v241, v241
	v_mul_f32_e32 v226, v226, v225
	v_mul_f32_e32 v227, v227, v225
	v_mul_f32_e32 v228, v228, v225
	v_mul_f32_e32 v229, v229, v225
	v_mul_f32_e32 v230, v230, v225
	v_mul_f32_e32 v231, v231, v225
	v_mul_f32_e32 v232, v232, v225
	v_mul_f32_e32 v233, v233, v225
	v_add_f32_e32 v234, 1.0, v234
	v_add_f32_e32 v235, 1.0, v235
	v_add_f32_e32 v236, 1.0, v236
	v_add_f32_e32 v237, 1.0, v237
	v_add_f32_e32 v238, 1.0, v238
	v_add_f32_e32 v239, 1.0, v239
	v_add_f32_e32 v240, 1.0, v240
	v_add_f32_e32 v241, 1.0, v241
	v_rcp_f32_e32 v234, v234
	v_rcp_f32_e32 v235, v235
	v_rcp_f32_e32 v236, v236
	v_rcp_f32_e32 v237, v237
	v_rcp_f32_e32 v238, v238
	v_rcp_f32_e32 v239, v239
	v_rcp_f32_e32 v240, v240
	v_rcp_f32_e32 v241, v241
	v_mul_f32_e32 v226, v226, v234
	v_mul_f32_e32 v227, v227, v235
	v_mul_f32_e32 v228, v228, v236
	v_mul_f32_e32 v229, v229, v237
	v_mul_f32_e32 v230, v230, v238
	v_mul_f32_e32 v231, v231, v239
	v_mul_f32_e32 v232, v232, v240
	v_mul_f32_e32 v233, v233, v241
	v_cvt_pk_bf16_f32 v246, v226, v227
	v_cvt_pk_bf16_f32 v247, v228, v229
	v_cvt_pk_bf16_f32 v248, v230, v231
	v_cvt_pk_bf16_f32 v249, v232, v233
	v_add_u32_e32 v4, 0xb0, v151
	v_lshrrev_b32_e32 v5, 3, v4
	v_and_or_b32 v5, v5, 14, s65
	v_lshlrev_b32_e32 v6, 6, v4
	v_lshlrev_b32_e32 v4, 2, v4
	v_and_or_b32 v6, v6, s64, v143
	v_lshlrev_b32_e32 v5, 10, v5
	v_and_b32_e32 v4, 32, v4
	v_bitop3_b32 v130, v6, v5, v4 bitop3:0xde
	v_lshl_add_u64 v[4:5], v[48:49], 0, v[130:131]
	global_store_dwordx4 v[4:5], v[246:249], off
	s_cbranch_vccnz .LBB0_1621
	s_and_saveexec_b64 s[4:5], s[2:3]
	s_cbranch_execz .LBB0_1631
	v_lshl_or_b32 v0, s46, 8, v208
	v_ashrrev_i32_e32 v1, 31, v0
	v_lshlrev_b64 v[0:1], 6, v[0:1]
	v_lshl_add_u64 v[12:13], s[10:11], 0, v[0:1]
	global_load_dwordx4 v[0:3], v[12:13], off
	global_load_dwordx4 v[4:7], v[12:13], off offset:16
	global_load_dwordx4 v[8:11], v[12:13], off offset:32
	s_nop 0
	global_load_dwordx4 v[12:15], v[12:13], off offset:48
	s_lshl_b32 s45, s72, 10
	s_and_b32 s45, s45, 0x400
	s_waitcnt vmcnt(0)
	v_pk_add_f32 v[2:3], v[2:3], v[6:7]
	v_pk_add_f32 v[0:1], v[0:1], v[4:5]
	v_pk_add_f32 v[4:5], v[10:11], v[14:15]
	v_pk_add_f32 v[6:7], v[8:9], v[12:13]
	v_pk_add_f32 v[2:3], v[2:3], v[4:5]
	v_pk_add_f32 v[0:1], v[0:1], v[6:7]
	s_nop 0
	v_pk_mov_b32 v[4:5], v[0:1], v[2:3] op_sel:[1,0]
	v_mov_b32_e32 v1, v3
	v_pk_add_f32 v[0:1], v[4:5], v[0:1]
	s_nop 0
	v_add_f32_e32 v0, v0, v1
	v_fmamk_f32 v0, v0, 0x3a800000, v150
	v_rsq_f32_e32 v0, v0
	v_add_u32_e32 v1, s45, v145
	ds_write_b32 v1, v0
